# attention unit prologue: forgetting-bias row staging loop unrolled 4 deep (four loads in flight per lane instead of one)
# speedup vs baseline: 1.0258x; 1.0046x over previous
.LBB0_2917:
	s_or_b64 exec, exec, s[14:15]
	s_waitcnt vmcnt(0) lgkmcnt(0)
	s_barrier
	s_waitcnt vmcnt(1)
	v_mov_b32_e32 v0, s72
	ds_read_b32 v0, v0
	s_bfe_u32 s54, s40, 0x10003
	s_mulk_i32 s54, 0x4100
	s_waitcnt lgkmcnt(0)
	v_readfirstlane_b32 s20, v0
	s_and_b32 s21, s20, -2
	s_lshl_b32 s33, s21, 6
	v_add_u32_e32 v0, s33, v3
	v_cmp_gt_i32_e32 vcc, s41, v0
	s_and_saveexec_b64 s[6:7], vcc
	s_cbranch_execz .LBB0_2922
	s_waitcnt vmcnt(0)
	v_lshl_add_u32 v2, v0, 2, s71
	v_mov_b32_e32 v7, 0
	v_mov_b32_e32 v9, 0
	v_mov_b32_e32 v11, 0
	v_mov_b32_e32 v5, 0x42c80000
	s_movk_i32 s16, 0xf0
.Lck_top:
	s_mov_b64 s[14:15], exec
	v_add_u32_e32 v6, 0x200, v0
	v_add_u32_e32 v8, 0x400, v0
	v_add_u32_e32 v10, 0x600, v0
	v_lshl_add_u64 v[12:13], v[0:1], 2, s[8:9]
	v_lshl_add_u64 v[14:15], v[6:7], 2, s[8:9]
	v_lshl_add_u64 v[16:17], v[8:9], 2, s[8:9]
	v_lshl_add_u64 v[18:19], v[10:11], 2, s[8:9]
	global_load_dword v12, v[12:13], off
	global_load_dword v14, v[14:15], off
	global_load_dword v16, v[16:17], off
	global_load_dword v18, v[18:19], off
	v_lshrrev_b32_e32 v20, 4, v0
	v_lshrrev_b32_e32 v21, 4, v6
	v_lshrrev_b32_e32 v22, 4, v8
	v_lshrrev_b32_e32 v23, 4, v10
	v_and_b32_e32 v20, 0xffffffc, v20
	v_and_b32_e32 v21, 0xffffffc, v21
	v_and_b32_e32 v22, 0xffffffc, v22
	v_and_b32_e32 v23, 0xffffffc, v23
	v_add_u32_e32 v20, 0x24c00, v20
	v_add_u32_e32 v21, 0x24c00, v21
	v_add_u32_e32 v22, 0x24c00, v22
	v_add_u32_e32 v23, 0x24c00, v23
	ds_read_b32 v20, v20
	ds_read_b32 v21, v21
	ds_read_b32 v22, v22
	ds_read_b32 v23, v23
	s_waitcnt vmcnt(0) lgkmcnt(0)
	v_add_f32_e32 v12, v12, v20
	v_add_f32_e32 v14, v14, v21
	v_add_f32_e32 v16, v16, v22
	v_add_f32_e32 v18, v18, v23
	v_cmp_gt_i32_e32 vcc, s16, v0
	v_mul_f32_e32 v12, 0x3fb8aa3b, v12
	v_mul_f32_e32 v14, 0x3fb8aa3b, v14
	v_mul_f32_e32 v16, 0x3fb8aa3b, v16
	v_mul_f32_e32 v18, 0x3fb8aa3b, v18
	v_cndmask_b32_e32 v12, v12, v5, vcc
	ds_write_b32 v2, v12
	v_cmp_gt_i32_e32 vcc, s41, v6
	s_and_b64 exec, s[14:15], vcc
	ds_write_b32 v2, v14 offset:2048
	v_cmp_gt_i32_e32 vcc, s41, v8
	s_and_b64 exec, s[14:15], vcc
	ds_write_b32 v2, v16 offset:4096
	v_cmp_gt_i32_e32 vcc, s41, v10
	s_and_b64 exec, s[14:15], vcc
	ds_write_b32 v2, v18 offset:6144
	s_mov_b64 exec, s[14:15]
	v_add_u32_e32 v0, 0x800, v0
	v_add_u32_e32 v2, 0x2000, v2
	v_cmp_gt_i32_e32 vcc, s41, v0
	s_and_b64 exec, exec, vcc
	s_cbranch_execnz .Lck_top
